# wave-specialised prologue: waves 4-7 stream x->fp16 rows [0,32768) while waves 0-3 run rope/twiddle/plain-weight routines in two passes
# speedup vs baseline: 1.5279x; 1.0120x over previous
; __device__ void p0_rope(const Args& a) {
;     float* rc = (float*)(a.ws + WS_ROPE); float* rsn = rc + 4096 * 32;
;     for (int idx = blockIdx.x * NTHREADS + threadIdx.x; idx < 4096 * 32; idx += gridDim.x * NTHREADS) {
;         const int i = idx & 31, pos = idx >> 5;
;         const float inv_freq = 1.0f / powf(10000.0f, (float)i * (1.0f / 32.0f));
;         const float ang = (float)pos * inv_freq;
;         float s, c; sincosf(ang, &s, &c);
;         rc[idx] = c; rsn[idx] = s;
;     }
; __global__ void __launch_bounds__(NTHREADS, 2) hymba_fwd(Args a) {
;     ...
;     if (IN(0)) { p0_mmat(a, lds); p0_rope(a); p0_twiddle(a); p_weights_plain(a); }
.LBB0_13:
	s_or_b64 exec, exec, s[4:5]
	s_barrier
	v_readfirstlane_b32 s100, v0
	s_nop 3
	s_cmp_ge_u32 s100, 0x100
	s_cbranch_scc1 .Lws_x
	s_mov_b32 s101, 0
.Lws_pass:
	s_lshl_b32 s3, s2, 9
	v_add_u32_e32 v1, s3, v0
	s_mov_b32 s3, 0x20000
	v_cmp_gt_i32_e32 vcc, s3, v1
	s_and_saveexec_b64 s[12:13], vcc
	s_cbranch_execz .LBB0_20
	v_and_b32_e32 v2, 31, v0
	v_cvt_f32_ubyte0_e32 v2, v2
	v_mul_f32_e32 v16, 0x3d000000, v2
	v_mov_b32_e32 v2, 0x461c4000
	v_cmp_eq_f32_e32 vcc, 0, v16
	s_mov_b32 s4, 0x3f2aaaab
	s_mov_b32 s5, 0x42b17218
	v_cndmask_b32_e64 v12, v2, 1.0, vcc
	v_frexp_mant_f32_e32 v2, v12
	v_cmp_gt_f32_e32 vcc, s4, v2
	s_mov_b32 s4, 0x3f317218
	s_mov_b32 s7, 0x3fb8aa3b
	v_cndmask_b32_e64 v3, 1.0, 2.0, vcc
	v_mul_f32_e32 v2, v2, v3
	v_add_f32_e32 v5, 1.0, v2
	v_rcp_f32_e32 v10, v5
	v_add_f32_e32 v3, -1.0, v5
	v_sub_f32_e32 v7, v2, v3
	v_add_f32_e32 v3, -1.0, v2
	v_mul_f32_e32 v11, v3, v10
	v_mul_f32_e32 v4, v5, v11
	v_fma_f32 v6, v11, v5, -v4
	v_fmac_f32_e32 v6, v11, v7
	v_add_f32_e32 v2, v4, v6
	v_sub_f32_e32 v5, v3, v2
	v_pk_add_f32 v[8:9], v[2:3], v[4:5] neg_lo:[0,1] neg_hi:[0,1]
	v_mov_b32_e32 v7, v2
	v_pk_add_f32 v[2:3], v[8:9], v[6:7] neg_lo:[0,1] neg_hi:[0,1]
	v_mov_b32_e32 v6, 0x3e91f4c4
	v_add_f32_e32 v2, v2, v3
	v_add_f32_e32 v2, v5, v2
	v_mul_f32_e32 v3, v10, v2
	v_add_f32_e32 v2, v11, v3
	v_sub_f32_e32 v4, v2, v11
	v_sub_f32_e32 v13, v3, v4
	v_mul_f32_e32 v3, v2, v2
	v_fma_f32 v5, v2, v2, -v3
	v_add_f32_e32 v4, v13, v13
	v_fmac_f32_e32 v5, v2, v4
	v_add_f32_e32 v4, v3, v5
	v_fmac_f32_e32 v6, 0x3e76c4e1, v4
	v_fmaak_f32 v6, v4, v6, 0x3ecccdef
	v_sub_f32_e32 v3, v4, v3
	v_sub_f32_e32 v14, v5, v3
	v_mul_f32_e32 v3, v4, v6
	v_fma_f32 v5, v4, v6, -v3
	v_fmac_f32_e32 v5, v14, v6
	v_add_f32_e32 v6, v3, v5
	v_add_f32_e32 v7, 0x3f2aaaaa, v6
	v_sub_f32_e32 v3, v6, v3
	v_sub_f32_e32 v3, v5, v3
	v_add_f32_e32 v5, 0xbf2aaaaa, v7
	v_add_f32_e32 v3, 0x31739010, v3
	v_sub_f32_e32 v5, v6, v5
	v_pk_mul_f32 v[8:9], v[2:3], v[4:5]
	v_pk_add_f32 v[10:11], v[2:3], v[4:5]
	v_fma_f32 v6, v4, v2, -v8
	v_fmac_f32_e32 v6, v4, v13
	v_mov_b32_e32 v9, v11
	v_fmac_f32_e32 v6, v14, v2
	v_pk_add_f32 v[4:5], v[8:9], v[6:7]
	v_ldexp_f32 v14, v13, 1
	v_sub_f32_e32 v3, v4, v8
	v_sub_f32_e32 v3, v6, v3
	v_sub_f32_e32 v6, v7, v5
	v_add_f32_e32 v9, v11, v6
	v_pk_mul_f32 v[6:7], v[4:5], v[4:5] op_sel:[0,1] op_sel_hi:[1,0]
	v_cvt_f64_f32_e32 v[10:11], v12
	v_frexp_exp_i32_f64_e32 v7, v[10:11]
	v_subbrev_co_u32_e32 v7, vcc, 0, v7, vcc
	v_cvt_f32_i32_e32 v7, v7
	v_fma_f32 v8, v4, v5, -v6
	v_fmac_f32_e32 v8, v4, v9
	v_fmac_f32_e32 v8, v3, v5
	v_mul_f32_e32 v4, 0x3f317218, v7
	v_fma_f32 v3, v7, s4, -v4
	v_fmamk_f32 v10, v7, 0xb102e308, v3
	v_ldexp_f32 v11, v2, 1
	v_add_f32_e32 v5, v6, v8
	v_pk_add_f32 v[2:3], v[4:5], v[10:11]
	v_mov_b32_e32 v12, v5
	v_mov_b32_e32 v13, v3
	v_mov_b32_e32 v7, v11
	v_pk_add_f32 v[6:7], v[12:13], v[6:7] neg_lo:[0,1] neg_hi:[0,1]
	v_mov_b32_e32 v9, v5
	v_pk_add_f32 v[6:7], v[8:9], v[6:7] neg_lo:[0,1] neg_hi:[0,1]
	v_mov_b32_e32 v11, v2
	v_add_f32_e32 v5, v14, v6
	v_add_f32_e32 v5, v5, v7
	v_pk_add_f32 v[6:7], v[2:3], v[4:5] neg_lo:[0,1] neg_hi:[0,1]
	v_pk_add_f32 v[8:9], v[2:3], v[4:5]
	v_mov_b32_e32 v4, v5
	v_mov_b32_e32 v7, v9
	v_pk_add_f32 v[12:13], v[10:11], v[6:7] neg_lo:[0,1] neg_hi:[0,1]
	v_pk_add_f32 v[6:7], v[10:11], v[6:7]
	v_mov_b32_e32 v5, v2
	v_pk_add_f32 v[10:11], v[6:7], v[2:3] op_sel:[1,0] op_sel_hi:[0,1] neg_lo:[0,1] neg_hi:[0,1]
	v_pk_add_f32 v[14:15], v[8:9], v[10:11] op_sel_hi:[1,0] neg_lo:[0,1] neg_hi:[0,1]
	v_mov_b32_e32 v8, v9
	v_mov_b32_e32 v9, v7
	v_pk_mov_b32 v[10:11], v[2:3], v[10:11] op_sel:[1,0]
	v_mov_b32_e32 v14, v12
	v_pk_add_f32 v[8:9], v[8:9], v[10:11] neg_lo:[0,1] neg_hi:[0,1]
	v_mov_b32_e32 v13, v7
	v_pk_add_f32 v[2:3], v[4:5], v[8:9] neg_lo:[0,1] neg_hi:[0,1]
	s_movk_i32 s4, 0x204
	v_pk_add_f32 v[4:5], v[14:15], v[2:3]
	s_mov_b32 s6, 0x7f800000
	v_pk_add_f32 v[8:9], v[4:5], v[4:5] op_sel:[0,1] op_sel_hi:[1,0]
	s_load_dword s3, s[0:1], 0x60
	v_pk_add_f32 v[6:7], v[6:7], v[8:9] op_sel:[1,0] op_sel_hi:[0,1]
	v_mov_b32_e32 v5, v6
	v_pk_add_f32 v[10:11], v[4:5], v[12:13] neg_lo:[0,1] neg_hi:[0,1]
	v_mov_b32_e32 v3, v8
	v_sub_f32_e32 v4, v4, v10
	v_pk_add_f32 v[2:3], v[2:3], v[10:11] neg_lo:[0,1] neg_hi:[0,1]
	v_sub_f32_e32 v4, v12, v4
	v_add_f32_e32 v2, v2, v4
	v_add_f32_e32 v2, v2, v3
	v_add_f32_e32 v3, v6, v2
	v_sub_f32_e32 v4, v3, v6
	v_sub_f32_e32 v2, v2, v4
	v_mul_f32_e32 v4, v16, v3
	v_fma_f32 v3, v16, v3, -v4
	v_fmac_f32_e32 v3, v16, v2
	v_add_f32_e32 v2, v4, v3
	v_cmp_class_f32_e64 vcc, v4, s4
	v_sub_f32_e32 v5, v2, v4
	v_sub_f32_e32 v3, v3, v5
	v_cndmask_b32_e32 v2, v2, v4, vcc
	v_mov_b32_e32 v4, 0x37000000
	v_cmp_eq_f32_e32 vcc, s5, v2
	s_add_u32 s30, s40, 0x20b00000
	s_addc_u32 s31, s41, 0
	v_cndmask_b32_e32 v4, 0, v4, vcc
	v_sub_f32_e32 v5, v2, v4
	v_mul_f32_e32 v6, 0x3fb8aa3b, v5
	v_fma_f32 v7, v5, s7, -v6
	v_rndne_f32_e32 v8, v6
	v_fmamk_f32 v7, v5, 0x32a5705f, v7
	v_sub_f32_e32 v6, v6, v8
	v_add_f32_e32 v6, v6, v7
	v_exp_f32_e32 v6, v6
	v_cvt_i32_f32_e32 v7, v8
	v_cmp_neq_f32_e64 vcc, |v2|, s6
	s_mov_b32 s7, 0xc2ce8ed0
	s_add_u32 s34, s40, 0x20b80000
	v_cndmask_b32_e32 v2, 0, v3, vcc
	v_ldexp_f32 v3, v6, v7
	v_cmp_ngt_f32_e32 vcc, s7, v5
	v_add_f32_e32 v2, v4, v2
	v_mov_b32_e32 v4, 0x7f800000
	v_cndmask_b32_e32 v3, 0, v3, vcc
	v_cmp_nlt_f32_e32 vcc, s5, v5
	s_addc_u32 s35, s41, 0
	s_waitcnt lgkmcnt(0)
	s_lshl_b32 s3, s3, 9
	v_cndmask_b32_e32 v3, v4, v3, vcc
	v_fma_f32 v2, v3, v2, v3
	v_cmp_class_f32_e64 vcc, v3, s4
	s_mov_b64 s[44:45], 0
	s_brev_b32 s9, 18
	v_cndmask_b32_e32 v2, v2, v3, vcc
	v_and_b32_e32 v3, 0x7fffffff, v2
	v_div_scale_f32 v4, s[4:5], v3, v3, 1.0
	v_rcp_f32_e32 v5, v4
	v_div_scale_f32 v3, vcc, 1.0, v3, 1.0
	s_mov_b32 s33, 0xfe5163ab
	v_fma_f32 v6, -v4, v5, 1.0
	v_fmac_f32_e32 v5, v6, v5
	v_mul_f32_e32 v6, v3, v5
	v_fma_f32 v7, -v4, v6, v3
	v_fmac_f32_e32 v6, v7, v5
	v_fma_f32 v3, -v4, v6, v3
	v_div_fmas_f32 v3, v3, v5, v6
	v_div_fixup_f32 v2, v3, |v2|, 1.0
	v_cmp_neq_f32_e32 vcc, s6, v16
	v_mov_b32_e32 v3, 0
	s_mov_b32 s48, 0x3c439041
	v_cndmask_b32_e32 v6, 0, v2, vcc
	s_mov_b32 s49, 0xdb629599
	s_mov_b32 s50, 0xf534ddc0
	s_mov_b32 s51, 0xfc2757d1
	s_mov_b32 s52, 0x4e441529
	s_mov_b32 s53, 0xa2f9836e
	s_mov_b32 s54, 0x3fc90fda
	s_mov_b32 s55, 0x3f22f983
	s_mov_b32 s56, 0xbfc90fda
	v_mov_b32_e32 v7, 0x3c0881c4
	v_mov_b32_e32 v8, 0xbab64f3b
	s_brev_b32 s57, 1
	s_movk_i32 s58, 0x1f8
	s_mov_b32 s59, 0x1ffff
	v_not_b32_e32 v9, 63
	v_not_b32_e32 v10, 31
	v_mov_b32_e32 v11, 0x7fc00000
	v_mov_b32_e32 v4, v1
	s_branch .LBB0_16

; __device__ void p0_xconv(const Args& a) {
;     f16* XH = (f16*)(a.ws + WS_XH); float* SS = (float*)(a.ws + WS_SS);
;     int tid_ = threadIdx.x; asm volatile("" : "+v"(tid_));
;     const int lane = tid_ & 63, wv = tid_ >> 6;
;     const int nwv = (int)gridDim.x * 8;
;     for (int row0 = (int)blockIdx.x * 8 + wv; row0 < MROWS; row0 += 4 * nwv) {
;         f32x4 v[4][4];
; #pragma unroll
;         for (int r = 0; r < 4; ++r) {
;             const int row = row0 + r * nwv;
;             if (row < MROWS) {
;                 const float* src = (row < ROWS_PROMPT) ? a.x_prompt + (size_t)row * DM : a.x_sample + (size_t)(row - ROWS_PROMPT) * DM;
; #pragma unroll
;                 for (int i = 0; i < 4; ++i) v[r][i] = __builtin_nontemporal_load((const f32x4*)(src + i * 256 + lane * 4));
.Lws_passend:
	s_cmp_lg_u32 s101, 0
	s_cbranch_scc1 .Lws_done
	s_mov_b32 s101, 1
	v_add_u32_e32 v0, 0x100, v0
	s_branch .Lws_pass
.Lws_done:
	v_add_u32_e32 v0, 0xffffff00, v0
	s_branch .LBB0_37
.Lws_x:
	v_writelane_b32 v255, s14, 10
	v_writelane_b32 v255, s15, 11
	v_writelane_b32 v255, s20, 12
	v_writelane_b32 v255, s21, 13
	v_writelane_b32 v255, s22, 14
	v_writelane_b32 v255, s23, 15
	v_mov_b32_e32 v1, v0
	s_mov_b32 s3, 0x8000
	v_ashrrev_i32_e32 v2, 6, v1
	v_lshl_add_u32 v78, s2, 2, v2
	v_add_u32_e32 v78, -4, v78
	v_cmp_gt_i32_e32 vcc, s3, v78
	s_and_saveexec_b64 s[20:21], vcc
	s_cbranch_execz .Lxc_111
	v_and_b32_e32 v1, 63, v1
	v_mov_b32_e32 v67, 0
	v_lshlrev_b32_e32 v66, 2, v1
	v_lshlrev_b32_e32 v2, 3, v1
	v_mov_b32_e32 v3, v67
	s_movk_i32 s36, 0x80
	v_lshl_add_u64 v[68:69], s[40:41], 0, v[2:3]
	v_lshl_add_u64 v[2:3], s[40:41], 0, v[66:67]
	s_mov_b64 s[4:5], 0x1f800000
	v_cmp_gt_u32_e32 vcc, 16, v1
	v_lshl_add_u64 v[70:71], v[2:3], 0, s[4:5]
	v_cmp_eq_u32_e64 s[4:5], 0, v1
	v_mbcnt_lo_u32_b32 v1, -1, 0
	v_mbcnt_hi_u32_b32 v2, -1, v1
	v_and_b32_e32 v1, 64, v2
	v_add_u32_e32 v3, 64, v1
	v_xor_b32_e32 v1, 1, v2
	v_cmp_lt_i32_e64 s[6:7], v1, v3
	v_xor_b32_e32 v4, 2, v2
	s_waitcnt lgkmcnt(0)
	s_lshl_b32 s9, s36, 3
	v_cndmask_b32_e64 v1, v2, v1, s[6:7]
	v_cmp_lt_i32_e64 s[6:7], v4, v3
	s_add_i32 s44, s9, s9
	v_lshlrev_b32_e32 v1, 2, v1
	v_cndmask_b32_e64 v4, v2, v4, s[6:7]
	v_lshlrev_b32_e32 v80, 2, v4
	v_xor_b32_e32 v4, 4, v2
	v_cmp_lt_i32_e64 s[6:7], v4, v3
	s_lshl_b32 s33, s36, 4
	s_mul_i32 s36, s36, 24
	v_cndmask_b32_e64 v4, v2, v4, s[6:7]
	v_lshlrev_b32_e32 v81, 2, v4
	v_xor_b32_e32 v4, 8, v2
	v_cmp_lt_i32_e64 s[6:7], v4, v3
	s_mov_b64 s[22:23], 0
	s_movk_i32 s37, 0x4000
	v_cndmask_b32_e64 v4, v2, v4, s[6:7]
	v_lshlrev_b32_e32 v82, 2, v4
	v_xor_b32_e32 v4, 16, v2
	v_cmp_lt_i32_e64 s[6:7], v4, v3
	v_mov_b32_e32 v85, s19
	v_mov_b32_e32 v86, s17
	v_cndmask_b32_e64 v4, v2, v4, s[6:7]
	v_lshlrev_b32_e32 v83, 2, v4
	v_xor_b32_e32 v4, 32, v2
	v_cmp_lt_i32_e64 s[6:7], v4, v3
	v_mov_b32_e32 v87, s18
	v_mov_b32_e32 v88, s16
	v_cndmask_b32_e64 v2, v2, v4, s[6:7]
	v_lshlrev_b32_e32 v84, 2, v2
	v_lshlrev_b32_e32 v66, 2, v66
	s_add_i32 s44, s44, s9
	s_mov_b32 s45, 0x7fff
	s_branch .Lxc_94

; __global__ void __launch_bounds__(NTHREADS, 2) hymba_fwd(Args a) {
;     ...
;     if (IN(0)) { p0_mmat(a, lds); p0_rope(a); p0_twiddle(a); p_weights_plain(a); }
.Lxc_111:
	s_or_b64 exec, exec, s[20:21]
	v_readlane_b32 s14, v255, 10
	v_readlane_b32 s15, v255, 11
	v_readlane_b32 s20, v255, 12
	v_readlane_b32 s21, v255, 13
	v_readlane_b32 s22, v255, 14
	v_readlane_b32 s23, v255, 15
	s_nop 3
	s_branch .LBB0_37

; __device__ void p0_xconv(const Args& a) {
;     f16* XH = (f16*)(a.ws + WS_XH); float* SS = (float*)(a.ws + WS_SS);
;     int tid_ = threadIdx.x; asm volatile("" : "+v"(tid_));
;     const int lane = tid_ & 63, wv = tid_ >> 6;
;     const int nwv = (int)gridDim.x * 8;
;     for (int row0 = (int)blockIdx.x * 8 + wv; row0 < MROWS; row0 += 4 * nwv) {
;         f32x4 v[4][4];
; #pragma unroll
;         for (int r = 0; r < 4; ++r) {
;             const int row = row0 + r * nwv;
;             if (row < MROWS) {
;                 const float* src = (row < ROWS_PROMPT) ? a.x_prompt + (size_t)row * DM : a.x_sample + (size_t)(row - ROWS_PROMPT) * DM;
; #pragma unroll
;                 for (int i = 0; i < 4; ++i) v[r][i] = __builtin_nontemporal_load((const f32x4*)(src + i * 256 + lane * 4));
.LBB0_91:
	v_mov_b32_e32 v1, v0
	s_barrier
	s_mov_b32 s3, 0xc000
	v_ashrrev_i32_e32 v2, 6, v1
	v_lshl_add_u32 v78, s2, 3, v2
	v_add_u32_e32 v78, 0x8000, v78
	v_cmp_gt_i32_e32 vcc, s3, v78
	s_and_saveexec_b64 s[20:21], vcc
	s_cbranch_execz .LBB0_111
	v_and_b32_e32 v1, 63, v1
	v_mov_b32_e32 v67, 0
	v_lshlrev_b32_e32 v66, 2, v1
	v_lshlrev_b32_e32 v2, 3, v1
	v_mov_b32_e32 v3, v67
	s_load_dword s36, s[4:5], 0x0
	v_lshl_add_u64 v[68:69], s[40:41], 0, v[2:3]
	v_lshl_add_u64 v[2:3], s[40:41], 0, v[66:67]
	s_mov_b64 s[4:5], 0x1f800000
	v_cmp_gt_u32_e32 vcc, 16, v1
	v_lshl_add_u64 v[70:71], v[2:3], 0, s[4:5]
	v_cmp_eq_u32_e64 s[4:5], 0, v1
	v_mbcnt_lo_u32_b32 v1, -1, 0
	v_mbcnt_hi_u32_b32 v2, -1, v1
	v_and_b32_e32 v1, 64, v2
	v_add_u32_e32 v3, 64, v1
	v_xor_b32_e32 v1, 1, v2
	v_cmp_lt_i32_e64 s[6:7], v1, v3
	v_xor_b32_e32 v4, 2, v2
	s_waitcnt lgkmcnt(0)
	s_lshl_b32 s9, s36, 3
	v_cndmask_b32_e64 v1, v2, v1, s[6:7]
	v_cmp_lt_i32_e64 s[6:7], v4, v3
	s_add_i32 s44, s9, s9
	v_lshlrev_b32_e32 v1, 2, v1
	v_cndmask_b32_e64 v4, v2, v4, s[6:7]
	v_lshlrev_b32_e32 v80, 2, v4
	v_xor_b32_e32 v4, 4, v2
	v_cmp_lt_i32_e64 s[6:7], v4, v3
	s_lshl_b32 s33, s36, 4
	s_mul_i32 s36, s36, 24
	v_cndmask_b32_e64 v4, v2, v4, s[6:7]
	v_lshlrev_b32_e32 v81, 2, v4
	v_xor_b32_e32 v4, 8, v2
	v_cmp_lt_i32_e64 s[6:7], v4, v3
	s_mov_b64 s[22:23], 0
	s_movk_i32 s37, 0x4000
	v_cndmask_b32_e64 v4, v2, v4, s[6:7]
	v_lshlrev_b32_e32 v82, 2, v4
	v_xor_b32_e32 v4, 16, v2
	v_cmp_lt_i32_e64 s[6:7], v4, v3
	v_mov_b32_e32 v85, s19
	v_mov_b32_e32 v86, s17
	v_cndmask_b32_e64 v4, v2, v4, s[6:7]
	v_lshlrev_b32_e32 v83, 2, v4
	v_xor_b32_e32 v4, 32, v2
	v_cmp_lt_i32_e64 s[6:7], v4, v3
	v_mov_b32_e32 v87, s18
	v_mov_b32_e32 v88, s16
	v_cndmask_b32_e64 v2, v2, v4, s[6:7]
	v_lshlrev_b32_e32 v84, 2, v2
	v_lshlrev_b32_e32 v66, 2, v66
	s_add_i32 s44, s44, s9
	s_mov_b32 s45, 0xbfff
	s_branch .LBB0_94
